# stick-breaking step: the eight K fragments of Q.K^T read up front into free registers, counted lgkmcnt per MFMA
# baseline (speedup 1.0000x reference)
; #define LAS __attribute__((address_space(3)))
; __device__ __forceinline__ int crow(int r, int hi) { return (r & 3) + 8 * (r >> 2) + 4 * hi; }
; #define MFMA32(a, b, c) __builtin_amdgcn_mfma_f32_32x32x16_bf16((a), (b), (c), 0, 0, 0)
; #define ATT_LOAD(set_, kt_) do { kreg[set_] = *(const GAS u32x4*)(ksrc + (size_t)(kt_) * 64 * 2048); \
;         _Pragma("unroll") for (int i_ = 0; i_ < NVC; ++i_) vreg[set_][i_] = *(const GAS u32x4*)(vsrc + (size_t)i_ * 64 * SEQ + (kt_) * 64); } while (0)
; template <int MODE, int DV> ...
;     ...
;         ATT_LOAD(hh, (kt - 2 > 0) ? kt - 2 : 0);
;         const int k0 = kt * 64;
;         const LAS unsigned char* sb = lds + hh * SB2_STAGE;
;         const bool active = ((MODE == 0) ? (k0 <= tw0 + 31) : (k0 < tw0 + 31)) && !wdone;
;         if (active) {
;             f32x16 p0, p1;
;             if (MODE == 0) {
;                 const float bb = slope2 * (float)(k0 + 4 * hi - t) - mrun;
; #pragma unroll
;                 for (int r = 0; r < 16; ++r) { const float c = __builtin_fmaf(slope2, (float)((r & 3) + 8 * (r >> 2)), bb); p0[r] = c; p1[r] = __builtin_fmaf(slope2, 32.0f, c); }
;             } else {
; #pragma unroll
;                 for (int r = 0; r < 16; ++r) { p0[r] = 0.f; p1[r] = 0.f; }
;             }
; #pragma unroll
;             for (int ds = 0; ds < 4; ++ds) {
;                 const bf16x8 k0f = *(const LAS bf16x8*)(sb + koff + ds * 32);
;                 const bf16x8 k1f = *(const LAS bf16x8*)(sb + koff + 32 * KSTR + ds * 32);
;                 p0 = MFMA32(k0f, qf[ds], p0); p1 = MFMA32(k1f, qf[ds], p1);
;     ...
;                 for (int r = 0; r < 16; ++r) {
;                     { const float z = p0[r]; const float e = __builtin_amdgcn_exp2f(-fabsf(z)); const float sp = fmaxf(-z, 0.f) + __builtin_amdgcn_logf(1.0f + e);
;                       const float lb = -sp; float lm = lb - z; if (diag && !(k0 + crow(r, hi) < t)) lm = 0.f; l0[r] = lm; ts += lm; p0[r] = lb + carry; }
;                     { const float z = p1[r]; const float e = __builtin_amdgcn_exp2f(-fabsf(z)); const float sp = fmaxf(-z, 0.f) + __builtin_amdgcn_logf(1.0f + e);
;                       const float lb = -sp; float lm = lb - z; if (diag && !(k0 + 32 + crow(r, hi) < t)) lm = 0.f; l1[r] = lm; ts += lm; p1[r] = lb + carry; }
.LBB0_445:
	s_max_i32 s3, s88, 2
	s_add_i32 s56, s3, -2
	s_lshl_b64 s[8:9], s[56:57], 18
	v_lshl_add_u64 v[34:35], v[126:127], 0, s[8:9]
	s_lshl_b32 s56, s56, 7
	v_lshl_add_u64 v[36:37], v[128:129], 0, s[56:57]
	global_load_dwordx4 v[106:109], v[34:35], off offset:3072
	global_load_dwordx4 v[110:113], v[36:37], off
	v_add_co_u32_e32 v34, vcc, s79, v34
	s_lshl_b32 s56, s88, 6
	s_nop 0
	v_addc_co_u32_e32 v35, vcc, 0, v35, vcc
	global_load_dwordx4 v[114:117], v[34:35], off offset:3072
	v_add_co_u32_e32 v34, vcc, 0x80000, v36
	s_cmp_ge_u32 s56, s90
	s_nop 0
	v_addc_co_u32_e32 v35, vcc, 0, v37, vcc
	global_load_dwordx4 v[118:121], v[34:35], off
	s_cselect_b64 s[8:9], -1, 0
	s_or_b64 s[8:9], s[8:9], s[6:7]
	s_and_b64 vcc, exec, s[8:9]
	s_cbranch_vccnz .LBB0_447
	v_add_u32_e32 v0, 0, v146
	ds_read_b128 v[196:199], v0
	ds_read_b128 v[200:203], v0 offset:32
	ds_read_b128 v[204:207], v0 offset:4608
	ds_read_b128 v[208:211], v0 offset:4640
	ds_read_b128 v[212:215], v0 offset:64
	ds_read_b128 v[216:219], v0 offset:96
	ds_read_b128 v[220:223], v0 offset:4672
	ds_read_b128 v[224:227], v0 offset:4704
	s_or_b32 s3, s56, 63
	s_cmp_lt_u32 s3, s87
	s_cselect_b64 s[64:65], -1, 0
	s_waitcnt lgkmcnt(7)
	v_mfma_f32_32x32x16_bf16 v[50:65], v[196:199], v[66:69], 0
	v_or_b32_e32 v166, s56, v148
	v_cmp_lt_u32_e64 s[6:7], v166, v137
	s_or_b64 s[6:7], s[64:65], s[6:7]
	s_mov_b32 s38, s36
	s_mov_b32 s39, s36
	s_mov_b32 s37, s36
	s_waitcnt lgkmcnt(5)
	v_mfma_f32_32x32x16_bf16 v[34:49], v[204:207], v[66:69], 0
	s_waitcnt lgkmcnt(6)
	v_mfma_f32_32x32x16_bf16 v[50:65], v[200:203], v[70:73], v[50:65]
	s_waitcnt lgkmcnt(4)
	v_mfma_f32_32x32x16_bf16 v[34:49], v[208:211], v[70:73], v[34:49]
	s_waitcnt lgkmcnt(3)
	v_mfma_f32_32x32x16_bf16 v[50:65], v[212:215], v[74:77], v[50:65]
	s_waitcnt lgkmcnt(1)
	v_mfma_f32_32x32x16_bf16 v[34:49], v[220:223], v[74:77], v[34:49]
	s_waitcnt lgkmcnt(2)
	v_mfma_f32_32x32x16_bf16 v[50:65], v[216:219], v[78:81], v[50:65]
	v_or_b32_e32 v150, s56, v139
	v_or_b32_e32 v151, 1, v150
	v_cmp_lt_u32_e64 s[8:9], v151, v137
	s_or_b64 s[8:9], s[64:65], s[8:9]
	v_cmp_lt_u32_e32 vcc, v150, v137
	s_or_b64 vcc, s[64:65], vcc
	s_nop 5
	v_exp_f32_e64 v131, -|v50|
	s_waitcnt lgkmcnt(0)
	v_mfma_f32_32x32x16_bf16 v[34:49], v[224:227], v[78:81], v[34:49]
	v_max_f32_e64 v130, -v50, -v50
	v_max_f32_e32 v130, 0, v130
	v_add_f32_e32 v131, 1.0, v131
	v_log_f32_e32 v132, v131
	v_max_f32_e64 v169, -v61, -v61
	s_nop 6
	v_max_f32_e64 v133, -v34, -v34
	v_max_f32_e32 v152, 0, v133
	v_exp_f32_e64 v133, -|v51|
	v_exp_f32_e64 v131, -|v34|
	v_add_f32_e32 v133, 1.0, v133
	v_log_f32_e32 v133, v133
	v_add_f32_e32 v131, 1.0, v131
	v_log_f32_e32 v154, v131
	v_max_f32_e64 v131, -v51, -v51
	v_max_f32_e32 v131, 0, v131
	v_pk_add_f32 v[132:133], v[130:131], v[132:133]
	v_exp_f32_e64 v130, -|v35|
	v_sub_f32_e64 v51, -v133, v51
	v_cndmask_b32_e64 v165, 0, v51, s[8:9]
	v_max_f32_e64 v51, -v35, -v35
	v_add_f32_e32 v130, 1.0, v130
	v_log_f32_e32 v155, v130
	v_max_f32_e32 v153, 0, v51
	v_or_b32_e32 v51, 1, v166
	v_cmp_lt_u32_e64 s[8:9], v51, v137
	v_pk_add_f32 v[130:131], v[152:153], v[154:155]
	v_sub_f32_e64 v50, -v132, v50
	v_sub_f32_e64 v34, -v130, v34
	v_cndmask_b32_e64 v158, 0, v34, s[6:7]
	v_sub_f32_e64 v35, -v131, v35
	s_or_b64 s[6:7], s[64:65], s[8:9]
	v_cndmask_b32_e64 v159, 0, v35, s[6:7]
	v_exp_f32_e64 v35, -|v52|
	v_cndmask_b32_e32 v164, 0, v50, vcc
	v_exp_f32_e64 v51, -|v36|
	v_add_f32_e32 v50, 0, v164
	v_add_f32_e32 v35, 1.0, v35
	v_add_f32_e32 v34, v50, v158
	v_log_f32_e32 v50, v35
	v_or_b32_e32 v35, 2, v150
	v_cmp_lt_u32_e64 s[6:7], v35, v137
	v_max_f32_e64 v35, -v36, -v36
	v_max_f32_e32 v152, 0, v35
	v_add_f32_e32 v35, 1.0, v51
	v_log_f32_e32 v154, v35
	v_exp_f32_e64 v35, -|v53|
	v_or_b32_e32 v51, 2, v166
	v_cmp_lt_u32_e64 s[8:9], v51, v137
	v_add_f32_e32 v34, v165, v34
	v_add_f32_e32 v35, 1.0, v35
	v_log_f32_e32 v51, v35
	v_add_f32_e32 v151, v159, v34
	v_max_f32_e64 v34, -v52, -v52
	v_max_f32_e64 v153, -v53, -v53
	v_max_f32_e32 v34, 0, v34
	v_max_f32_e32 v35, 0, v153
	v_pk_add_f32 v[50:51], v[34:35], v[50:51]
	v_exp_f32_e64 v35, -|v37|
	v_or_b32_e32 v153, 3, v150
	v_cmp_lt_u32_e64 s[10:11], v153, v137
	v_sub_f32_e64 v34, -v50, v52
	v_add_f32_e32 v35, 1.0, v35
	s_or_b64 s[6:7], s[64:65], s[6:7]
	v_log_f32_e32 v155, v35
	v_cndmask_b32_e64 v180, 0, v34, s[6:7]
	v_sub_f32_e64 v34, -v51, v53
	s_or_b64 s[6:7], s[64:65], s[10:11]
	v_cndmask_b32_e64 v163, 0, v34, s[6:7]
	v_max_f32_e64 v34, -v37, -v37
	v_max_f32_e32 v153, 0, v34
	v_or_b32_e32 v34, 3, v166
	v_cmp_lt_u32_e64 s[6:7], v34, v137
	v_pk_add_f32 v[34:35], v[152:153], v[154:155]
	s_or_b64 s[8:9], s[64:65], s[8:9]
	v_sub_f32_e64 v36, -v34, v36
	v_cndmask_b32_e64 v167, 0, v36, s[8:9]
	v_sub_f32_e64 v36, -v35, v37
	v_exp_f32_e64 v37, -|v54|
	v_exp_f32_e64 v53, -|v38|
	s_or_b64 s[6:7], s[64:65], s[6:7]
	v_cndmask_b32_e64 v168, 0, v36, s[6:7]
	v_add_f32_e32 v37, 1.0, v37
	v_log_f32_e32 v52, v37
	v_or_b32_e32 v37, 8, v150
	v_cmp_lt_u32_e64 s[6:7], v37, v137
	v_max_f32_e64 v37, -v38, -v38
	v_max_f32_e32 v152, 0, v37
	v_add_f32_e32 v37, 1.0, v53
	v_log_f32_e32 v154, v37
	v_exp_f32_e64 v37, -|v55|
	v_or_b32_e32 v53, 8, v166
	v_cmp_lt_u32_e64 s[8:9], v53, v137
	v_add_f32_e32 v162, v180, v151
	v_add_f32_e32 v37, 1.0, v37
	v_log_f32_e32 v53, v37
	v_max_f32_e64 v36, -v54, -v54
	v_max_f32_e64 v151, -v55, -v55
	v_max_f32_e32 v36, 0, v36
	v_max_f32_e32 v37, 0, v151
	v_pk_add_f32 v[52:53], v[36:37], v[52:53]
	v_exp_f32_e64 v37, -|v39|
	v_or_b32_e32 v151, 9, v150
	v_cmp_lt_u32_e64 s[10:11], v151, v137
	v_sub_f32_e64 v36, -v52, v54
	v_add_f32_e32 v37, 1.0, v37
	s_or_b64 s[6:7], s[64:65], s[6:7]
	v_log_f32_e32 v155, v37
	v_cndmask_b32_e64 v184, 0, v36, s[6:7]
; __device__ __forceinline__ int crow(int r, int hi) { return (r & 3) + 8 * (r >> 2) + 4 * hi; }
; template <int MODE, int DV> ...
;     ...
;                 for (int r = 0; r < 16; ++r) {
;                     { const float z = p0[r]; const float e = __builtin_amdgcn_exp2f(-fabsf(z)); const float sp = fmaxf(-z, 0.f) + __builtin_amdgcn_logf(1.0f + e);
;                       const float lb = -sp; float lm = lb - z; if (diag && !(k0 + crow(r, hi) < t)) lm = 0.f; l0[r] = lm; ts += lm; p0[r] = lb + carry; }
;                     { const float z = p1[r]; const float e = __builtin_amdgcn_exp2f(-fabsf(z)); const float sp = fmaxf(-z, 0.f) + __builtin_amdgcn_logf(1.0f + e);
;                       const float lb = -sp; float lm = lb - z; if (diag && !(k0 + 32 + crow(r, hi) < t)) lm = 0.f; l1[r] = lm; ts += lm; p1[r] = lb + carry; }
;                 }
	v_sub_f32_e64 v36, -v53, v55
	s_or_b64 s[6:7], s[64:65], s[10:11]
	v_cndmask_b32_e64 v185, 0, v36, s[6:7]
	v_max_f32_e64 v36, -v39, -v39
	v_max_f32_e32 v153, 0, v36
	v_or_b32_e32 v36, 9, v166
	v_cmp_lt_u32_e64 s[10:11], v36, v137
	v_pk_add_f32 v[36:37], v[152:153], v[154:155]
	s_or_b64 s[8:9], s[64:65], s[8:9]
	v_sub_f32_e64 v38, -v36, v38
	v_cndmask_b32_e64 v186, 0, v38, s[8:9]
	v_sub_f32_e64 v38, -v37, v39
	v_exp_f32_e64 v39, -|v56|
	v_exp_f32_e64 v55, -|v40|
	s_or_b64 s[8:9], s[64:65], s[10:11]
	v_cndmask_b32_e64 v187, 0, v38, s[8:9]
	v_add_f32_e32 v39, 1.0, v39
	v_log_f32_e32 v54, v39
	v_or_b32_e32 v39, 10, v150
	v_cmp_lt_u32_e64 s[8:9], v39, v137
	v_max_f32_e64 v39, -v40, -v40
	v_max_f32_e32 v154, 0, v39
	v_add_f32_e32 v39, 1.0, v55
	v_log_f32_e32 v160, v39
	v_exp_f32_e64 v39, -|v57|
	v_or_b32_e32 v55, 10, v166
	v_cmp_lt_u32_e64 s[12:13], v55, v137
	v_max_f32_e64 v38, -v56, -v56
	v_add_f32_e32 v39, 1.0, v39
	v_log_f32_e32 v55, v39
	v_max_f32_e64 v151, -v57, -v57
	v_max_f32_e32 v38, 0, v38
	v_max_f32_e32 v39, 0, v151
	v_pk_add_f32 v[54:55], v[38:39], v[54:55]
	v_exp_f32_e64 v39, -|v41|
	v_or_b32_e32 v151, 11, v150
	v_cmp_lt_u32_e64 s[14:15], v151, v137
	v_sub_f32_e64 v38, -v54, v56
	v_add_f32_e32 v39, 1.0, v39
	s_or_b64 s[10:11], s[64:65], s[8:9]
	v_log_f32_e32 v161, v39
	v_cndmask_b32_e64 v151, 0, v38, s[10:11]
	v_sub_f32_e64 v38, -v55, v57
	s_or_b64 s[8:9], s[64:65], s[14:15]
	v_cndmask_b32_e64 v152, 0, v38, s[8:9]
	v_max_f32_e64 v38, -v41, -v41
	v_max_f32_e32 v155, 0, v38
	v_or_b32_e32 v38, 11, v166
	v_cmp_lt_u32_e64 s[14:15], v38, v137
	v_pk_add_f32 v[38:39], v[154:155], v[160:161]
	s_or_b64 s[12:13], s[64:65], s[12:13]
	v_sub_f32_e64 v40, -v38, v40
	v_cndmask_b32_e64 v153, 0, v40, s[12:13]
	v_sub_f32_e64 v40, -v39, v41
	v_exp_f32_e64 v41, -|v58|
	v_exp_f32_e64 v57, -|v42|
	s_or_b64 s[12:13], s[64:65], s[14:15]
	v_cndmask_b32_e64 v154, 0, v40, s[12:13]
	v_add_f32_e32 v41, 1.0, v41
	v_log_f32_e32 v56, v41
	v_or_b32_e32 v41, 16, v150
	v_cmp_lt_u32_e64 s[12:13], v41, v137
	v_max_f32_e64 v41, -v42, -v42
	v_max_f32_e32 v160, 0, v41
	v_add_f32_e32 v41, 1.0, v57
	v_log_f32_e32 v170, v41
	v_exp_f32_e64 v41, -|v59|
	v_or_b32_e32 v57, 16, v166
	v_cmp_lt_u32_e64 s[14:15], v57, v137
	v_max_f32_e64 v40, -v58, -v58
	v_add_f32_e32 v41, 1.0, v41
	v_log_f32_e32 v57, v41
	v_max_f32_e64 v155, -v59, -v59
	v_max_f32_e32 v40, 0, v40
	v_max_f32_e32 v41, 0, v155
	v_pk_add_f32 v[56:57], v[40:41], v[56:57]
	v_exp_f32_e64 v41, -|v43|
	v_or_b32_e32 v155, 17, v150
	v_cmp_lt_u32_e64 s[16:17], v155, v137
	v_sub_f32_e64 v40, -v56, v58
	v_add_f32_e32 v41, 1.0, v41
	s_or_b64 s[12:13], s[64:65], s[12:13]
	v_log_f32_e32 v171, v41
	v_cndmask_b32_e64 v157, 0, v40, s[12:13]
	v_sub_f32_e64 v40, -v57, v59
	s_or_b64 s[12:13], s[64:65], s[16:17]
	v_cndmask_b32_e64 v155, 0, v40, s[12:13]
	v_max_f32_e64 v40, -v43, -v43
	v_max_f32_e32 v161, 0, v40
	v_or_b32_e32 v40, 17, v166
	v_cmp_lt_u32_e64 s[16:17], v40, v137
	v_pk_add_f32 v[40:41], v[160:161], v[170:171]
	s_or_b64 s[14:15], s[64:65], s[14:15]
	v_sub_f32_e64 v42, -v40, v42
	v_cndmask_b32_e64 v160, 0, v42, s[14:15]
	v_sub_f32_e64 v42, -v41, v43
	v_exp_f32_e64 v43, -|v60|
	v_exp_f32_e64 v59, -|v44|
	s_or_b64 s[14:15], s[64:65], s[16:17]
	v_cndmask_b32_e64 v161, 0, v42, s[14:15]
	v_add_f32_e32 v43, 1.0, v43
	v_log_f32_e32 v58, v43
	v_or_b32_e32 v43, 18, v150
	v_cmp_lt_u32_e64 s[14:15], v43, v137
	v_max_f32_e64 v43, -v44, -v44
	v_max_f32_e32 v172, 0, v43
	v_add_f32_e32 v43, 1.0, v59
	v_log_f32_e32 v174, v43
	v_exp_f32_e64 v43, -|v61|
	v_or_b32_e32 v59, 18, v166
	v_cmp_lt_u32_e64 s[18:19], v59, v137
	v_max_f32_e64 v42, -v60, -v60
	v_add_f32_e32 v43, 1.0, v43
	v_log_f32_e32 v59, v43
	v_max_f32_e32 v42, 0, v42
	v_max_f32_e32 v43, 0, v169
	v_or_b32_e32 v169, 19, v150
	v_pk_add_f32 v[42:43], v[42:43], v[58:59]
	v_exp_f32_e64 v59, -|v45|
	v_cmp_lt_u32_e64 s[20:21], v169, v137
	v_sub_f32_e64 v58, -v42, v60
	s_or_b64 s[16:17], s[64:65], s[14:15]
	v_add_f32_e32 v59, 1.0, v59
	v_log_f32_e32 v175, v59
	v_cndmask_b32_e64 v169, 0, v58, s[16:17]
	v_sub_f32_e64 v58, -v43, v61
	s_or_b64 s[14:15], s[64:65], s[20:21]
	v_cndmask_b32_e64 v170, 0, v58, s[14:15]
	v_max_f32_e64 v58, -v45, -v45
	v_max_f32_e32 v173, 0, v58
	v_pk_add_f32 v[172:173], v[172:173], v[174:175]
	s_or_b64 s[18:19], s[64:65], s[18:19]
	v_sub_f32_e64 v44, -v172, v44
	v_cndmask_b32_e64 v171, 0, v44, s[18:19]
	v_sub_f32_e64 v44, -v173, v45
	v_exp_f32_e64 v45, -|v62|
	v_or_b32_e32 v58, 19, v166
	v_exp_f32_e64 v59, -|v46|
	v_cmp_lt_u32_e64 s[20:21], v58, v137
	v_add_f32_e32 v45, 1.0, v45
	s_or_b64 s[18:19], s[64:65], s[20:21]
	v_log_f32_e32 v58, v45
	v_or_b32_e32 v45, 24, v150
	v_cndmask_b32_e64 v188, 0, v44, s[18:19]
	v_cmp_lt_u32_e64 s[18:19], v45, v137
	v_max_f32_e64 v45, -v46, -v46
	v_max_f32_e32 v60, 0, v45
	v_add_f32_e32 v45, 1.0, v59
	v_log_f32_e32 v174, v45
	v_exp_f32_e64 v45, -|v63|
	v_or_b32_e32 v59, 24, v166
	v_cmp_lt_u32_e64 s[24:25], v59, v137
	v_max_f32_e64 v44, -v62, -v62
	v_add_f32_e32 v45, 1.0, v45
	v_log_f32_e32 v59, v45
	v_max_f32_e64 v61, -v63, -v63
	v_max_f32_e32 v44, 0, v44
	v_max_f32_e32 v45, 0, v61
	v_pk_add_f32 v[44:45], v[44:45], v[58:59]
	v_exp_f32_e64 v59, -|v47|
	v_or_b32_e32 v61, 25, v150
	v_cmp_lt_u32_e64 s[20:21], v61, v137
	v_sub_f32_e64 v58, -v44, v62
	v_add_f32_e32 v59, 1.0, v59
	s_or_b64 s[22:23], s[64:65], s[18:19]
	v_log_f32_e32 v175, v59
	v_cndmask_b32_e64 v189, 0, v58, s[22:23]
	v_sub_f32_e64 v58, -v45, v63
	s_or_b64 s[20:21], s[64:65], s[20:21]
	v_cndmask_b32_e64 v190, 0, v58, s[20:21]
	v_max_f32_e64 v58, -v47, -v47
	v_max_f32_e32 v61, 0, v58
	v_pk_add_f32 v[174:175], v[60:61], v[174:175]
	s_or_b64 s[24:25], s[64:65], s[24:25]
; __device__ __forceinline__ int crow(int r, int hi) { return (r & 3) + 8 * (r >> 2) + 4 * hi; }
; #define MFMA32(a, b, c) __builtin_amdgcn_mfma_f32_32x32x16_bf16((a), (b), (c), 0, 0, 0)
; template <int MODE, int DV> ...
;     ...
;                 for (int r = 0; r < 16; ++r) {
;                     { const float z = p0[r]; const float e = __builtin_amdgcn_exp2f(-fabsf(z)); const float sp = fmaxf(-z, 0.f) + __builtin_amdgcn_logf(1.0f + e);
;                       const float lb = -sp; float lm = lb - z; if (diag && !(k0 + crow(r, hi) < t)) lm = 0.f; l0[r] = lm; ts += lm; p0[r] = lb + carry; }
;                     { const float z = p1[r]; const float e = __builtin_amdgcn_exp2f(-fabsf(z)); const float sp = fmaxf(-z, 0.f) + __builtin_amdgcn_logf(1.0f + e);
;                       const float lb = -sp; float lm = lb - z; if (diag && !(k0 + 32 + crow(r, hi) < t)) lm = 0.f; l1[r] = lm; ts += lm; p1[r] = lb + carry; }
;                 }
;                 const bf16x8 L0a = pack8(l0, 0), L0b = pack8(l0, 8), L1a = pack8(l1, 0), L1b = pack8(l1, 8);
;                 p0 = MFMA32(ut0, L0a, p0); p0 = MFMA32(ut1, L0b, p0); p0 = MFMA32(uone, L1a, p0); p0 = MFMA32(uone, L1b, p0);
;                 p1 = MFMA32(ut0, L1a, p1); p1 = MFMA32(ut1, L1b, p1);
; #pragma unroll
;                 for (int r = 0; r < 16; ++r) {
;                     float a0 = __builtin_amdgcn_exp2f(p0[r]), a1 = __builtin_amdgcn_exp2f(p1[r]);
;                     if (diag) { if (!(k0 + crow(r, hi) < t)) a0 = 0.f; if (!(k0 + 32 + crow(r, hi) < t)) a1 = 0.f; }
;                     p0[r] = a0; p1[r] = a1;
;                 }
	v_sub_f32_e64 v46, -v174, v46
	v_cndmask_b32_e64 v191, 0, v46, s[24:25]
	v_sub_f32_e64 v46, -v175, v47
	v_exp_f32_e64 v47, -|v64|
	v_or_b32_e32 v58, 25, v166
	v_exp_f32_e64 v59, -|v48|
	v_cmp_lt_u32_e64 s[18:19], v58, v137
	v_add_f32_e32 v47, 1.0, v47
	s_or_b64 s[18:19], s[64:65], s[18:19]
	v_log_f32_e32 v58, v47
	v_or_b32_e32 v47, 26, v150
	v_cndmask_b32_e64 v192, 0, v46, s[18:19]
	v_cmp_lt_u32_e64 s[18:19], v47, v137
	v_max_f32_e64 v47, -v48, -v48
	v_max_f32_e32 v176, 0, v47
	v_add_f32_e32 v47, 1.0, v59
	v_log_f32_e32 v178, v47
	v_exp_f32_e64 v47, -|v65|
	v_or_b32_e32 v59, 26, v166
	v_max_f32_e64 v60, -v65, -v65
	v_cmp_lt_u32_e64 s[28:29], v59, v137
	v_add_f32_e32 v47, 1.0, v47
	v_log_f32_e32 v59, v47
	v_max_f32_e32 v47, 0, v60
	v_or_b32_e32 v60, 27, v150
	v_cmp_lt_u32_e64 s[30:31], v60, v137
	v_sub_f32_e32 v60, v149, v42
	v_exp_f32_e64 v42, -|v49|
	v_max_f32_e64 v46, -v64, -v64
	v_max_f32_e32 v46, 0, v46
	v_sub_f32_e32 v61, v149, v43
	v_add_f32_e32 v42, 1.0, v42
	v_log_f32_e32 v179, v42
	v_max_f32_e64 v43, -v49, -v49
	v_pk_add_f32 v[46:47], v[46:47], v[58:59]
	v_max_f32_e32 v177, 0, v43
	v_or_b32_e32 v42, 27, v166
	v_sub_f32_e64 v58, -v46, v64
	s_or_b64 s[24:25], s[64:65], s[18:19]
	s_or_b64 s[18:19], s[64:65], s[30:31]
	v_cmp_lt_u32_e64 s[30:31], v42, v137
	v_pk_add_f32 v[42:43], v[176:177], v[178:179]
	v_cndmask_b32_e64 v193, 0, v58, s[24:25]
	v_sub_f32_e64 v58, -v47, v65
	v_sub_f32_e32 v62, v149, v44
	v_sub_f32_e64 v44, -v42, v48
	s_or_b64 s[28:29], s[64:65], s[28:29]
	v_cndmask_b32_e64 v194, 0, v58, s[18:19]
	v_sub_f32_e32 v58, v149, v56
	v_sub_f32_e32 v56, v149, v54
	v_sub_f32_e32 v54, v149, v52
	v_sub_f32_e32 v52, v149, v50
	v_sub_f32_e32 v50, v149, v132
	v_cndmask_b32_e64 v132, 0, v44, s[28:29]
	v_sub_f32_e64 v44, -v43, v49
	s_or_b64 s[28:29], s[64:65], s[30:31]
	v_sub_f32_e32 v65, v149, v47
	v_sub_f32_e32 v64, v149, v46
	v_sub_f32_e32 v63, v149, v45
	v_sub_f32_e32 v59, v149, v57
	v_sub_f32_e32 v57, v149, v55
	v_sub_f32_e32 v55, v149, v53
	v_sub_f32_e32 v53, v149, v51
	v_sub_f32_e32 v51, v149, v133
	v_cndmask_b32_e64 v133, 0, v44, s[28:29]
	v_sub_f32_e32 v49, v149, v43
	v_sub_f32_e32 v48, v149, v42
	v_cvt_pk_bf16_f32 v42, v164, v165
	v_cvt_pk_bf16_f32 v43, v180, v163
	v_cvt_pk_bf16_f32 v44, v184, v185
	v_cvt_pk_bf16_f32 v45, v151, v152
	v_sub_f32_e32 v47, v149, v175
	v_sub_f32_e32 v46, v149, v174
	v_mfma_f32_32x32x16_bf16 v[50:65], v[98:101], v[42:45], v[50:65]
	v_sub_f32_e32 v45, v149, v173
	v_sub_f32_e32 v44, v149, v172
	v_cvt_pk_bf16_f32 v172, v157, v155
	v_cvt_pk_bf16_f32 v173, v169, v170
	v_cvt_pk_bf16_f32 v174, v189, v190
	v_cvt_pk_bf16_f32 v175, v193, v194
	v_cvt_pk_bf16_f32 v176, v158, v159
	v_cvt_pk_bf16_f32 v177, v167, v168
	v_mfma_f32_32x32x16_bf16 v[50:65], v[102:105], v[172:175], v[50:65]
	v_mov_b64_e32 v[174:175], s[38:39]
	v_mov_b64_e32 v[172:173], s[36:37]
	v_cvt_pk_bf16_f32 v178, v186, v187
	v_cvt_pk_bf16_f32 v179, v153, v154
	v_sub_f32_e32 v43, v149, v41
	v_sub_f32_e32 v42, v149, v40
	v_sub_f32_e32 v41, v149, v39
	v_mfma_f32_32x32x16_bf16 v[50:65], v[172:175], v[176:179], v[50:65]
	v_sub_f32_e32 v40, v149, v38
	v_sub_f32_e32 v39, v149, v37
	v_sub_f32_e32 v38, v149, v36
	v_sub_f32_e32 v37, v149, v35
	v_sub_f32_e32 v36, v149, v34
	v_sub_f32_e32 v35, v149, v131
	v_sub_f32_e32 v34, v149, v130
	v_cvt_pk_bf16_f32 v180, v160, v161
	v_cvt_pk_bf16_f32 v181, v171, v188
	v_mfma_f32_32x32x16_bf16 v[34:49], v[98:101], v[176:179], v[34:49]
	v_cvt_pk_bf16_f32 v182, v191, v192
	v_cvt_pk_bf16_f32 v183, v132, v133
	v_or_b32_e32 v131, 32, v150
	v_cmp_lt_u32_e64 s[28:29], v131, v137
	v_add_f32_e32 v130, v167, v162
	v_add_f32_e32 v130, v163, v130
	v_add_f32_e32 v130, v168, v130
	v_mfma_f32_32x32x16_bf16 v[50:65], v[172:175], v[180:183], v[50:65]
	v_add_f32_e32 v130, v184, v130
	v_add_f32_e32 v130, v186, v130
	v_add_f32_e32 v130, v185, v130
	v_add_f32_e32 v130, v187, v130
	v_mfma_f32_32x32x16_bf16 v[34:49], v[102:105], v[180:183], v[34:49]
	s_nop 6
	v_exp_f32_e32 v50, v50
	v_exp_f32_e32 v65, v65
	v_cndmask_b32_e32 v50, 0, v50, vcc
	s_or_b64 vcc, s[64:65], s[28:29]
	s_nop 0
	v_exp_f32_e32 v34, v34
	v_exp_f32_e32 v35, v35
	v_cndmask_b32_e32 v131, 0, v34, vcc
	v_exp_f32_e32 v34, v51
	v_or_b32_e32 v51, s56, v141
	v_cmp_lt_u32_e32 vcc, v51, v137
	v_or_b32_e32 v51, 32, v51
	v_cmp_lt_u32_e64 s[28:29], v51, v137
	s_or_b64 vcc, s[64:65], vcc
	v_cndmask_b32_e32 v51, 0, v34, vcc
	s_or_b64 vcc, s[64:65], s[28:29]
	v_exp_f32_e32 v34, v52
	v_cndmask_b32_e32 v158, 0, v35, vcc
	v_exp_f32_e32 v35, v36
	v_or_b32_e32 v36, s56, v142
	v_cmp_lt_u32_e32 vcc, v36, v137
	v_or_b32_e32 v36, 32, v36
	s_or_b64 vcc, s[64:65], vcc
	v_cmp_lt_u32_e64 s[28:29], v36, v137
	v_cndmask_b32_e32 v52, 0, v34, vcc
	v_exp_f32_e32 v34, v53
	s_or_b64 vcc, s[64:65], s[28:29]
	v_or_b32_e32 v36, s56, v143
	v_cndmask_b32_e32 v159, 0, v35, vcc
	v_exp_f32_e32 v35, v37
	v_cmp_lt_u32_e32 vcc, v36, v137
	v_or_b32_e32 v36, 32, v36
	s_or_b64 vcc, s[64:65], vcc
	v_cmp_lt_u32_e64 s[28:29], v36, v137
	v_cndmask_b32_e32 v53, 0, v34, vcc
	v_exp_f32_e32 v34, v54
	s_or_b64 vcc, s[64:65], s[28:29]
	v_or_b32_e32 v36, s56, v144
; #define LAS __attribute__((address_space(3)))
; __device__ __forceinline__ int crow(int r, int hi) { return (r & 3) + 8 * (r >> 2) + 4 * hi; }
; #define MFMA32(a, b, c) __builtin_amdgcn_mfma_f32_32x32x16_bf16((a), (b), (c), 0, 0, 0)
; __device__ __forceinline__ float xhalf_sum(float m) { auto rr = __builtin_amdgcn_permlane32_swap(__float_as_uint(m), __float_as_uint(m), false, false); return __uint_as_float(rr[0]) + __uint_as_float(rr[1]); }
; template <int MODE, int DV> ...
;     ...
;                 for (int r = 0; r < 16; ++r) {
;                     float a0 = __builtin_amdgcn_exp2f(p0[r]), a1 = __builtin_amdgcn_exp2f(p1[r]);
;                     if (diag) { if (!(k0 + crow(r, hi) < t)) a0 = 0.f; if (!(k0 + 32 + crow(r, hi) < t)) a1 = 0.f; }
;                     p0[r] = a0; p1[r] = a1;
;                 }
;                 ts = xhalf_sum(ts);
;                 carry += ts;
;                 pf0 = pack8(p0, 0); pf1 = pack8(p0, 8); pf2 = pack8(p1, 0); pf3 = pack8(p1, 8);
;                 wdone = __all(carry < THR) != 0;
;             }
; #pragma unroll
;             for (int d = 0; d < NDB; ++d) {
;                 const LAS unsigned char* vb = sb + 2 * SB2_KB + d * 32 * KSTR + koff;
;                 const bf16x8 v0 = *(const LAS bf16x8*)(vb), v1 = *(const LAS bf16x8*)(vb + 32), v2 = *(const LAS bf16x8*)(vb + 64), v3 = *(const LAS bf16x8*)(vb + 96);
;                 o[d] = MFMA32(v0, pf0, o[d]); o[d] = MFMA32(v1, pf1, o[d]); o[d] = MFMA32(v2, pf2, o[d]); o[d] = MFMA32(v3, pf3, o[d]);
;             }
	v_cndmask_b32_e32 v162, 0, v35, vcc
	v_exp_f32_e32 v35, v38
	v_cmp_lt_u32_e32 vcc, v36, v137
	v_or_b32_e32 v36, 32, v36
	s_or_b64 vcc, s[64:65], vcc
	v_cmp_lt_u32_e64 s[28:29], v36, v137
	v_cndmask_b32_e32 v54, 0, v34, vcc
	v_exp_f32_e32 v34, v55
	s_or_b64 vcc, s[64:65], s[28:29]
	v_cndmask_b32_e32 v163, 0, v35, vcc
	v_exp_f32_e32 v35, v39
	v_or_b32_e32 v36, 41, v150
	v_cmp_lt_u32_e32 vcc, v36, v137
	v_cndmask_b32_e64 v55, 0, v34, s[6:7]
	v_exp_f32_e32 v34, v56
	s_or_b64 vcc, s[64:65], vcc
	v_cndmask_b32_e32 v164, 0, v35, vcc
	v_exp_f32_e32 v35, v40
	v_or_b32_e32 v36, 42, v150
	v_cmp_lt_u32_e32 vcc, v36, v137
	v_cndmask_b32_e64 v56, 0, v34, s[10:11]
	v_exp_f32_e32 v34, v57
	s_or_b64 vcc, s[64:65], vcc
	v_cndmask_b32_e32 v165, 0, v35, vcc
	v_exp_f32_e32 v35, v41
	v_or_b32_e32 v36, 43, v150
	v_cmp_lt_u32_e32 vcc, v36, v137
	v_cndmask_b32_e64 v41, 0, v34, s[8:9]
	v_exp_f32_e32 v34, v58
	s_or_b64 vcc, s[64:65], vcc
	v_or_b32_e32 v36, s56, v140
	v_cndmask_b32_e32 v57, 0, v35, vcc
	v_cmp_lt_u32_e32 vcc, v36, v137
	v_exp_f32_e32 v35, v42
	s_or_b64 vcc, s[64:65], vcc
	v_or_b32_e32 v36, 32, v36
	v_cndmask_b32_e32 v58, 0, v34, vcc
	v_exp_f32_e32 v34, v59
	v_cmp_lt_u32_e64 s[6:7], v36, v137
	s_or_b64 vcc, s[64:65], s[6:7]
	v_cndmask_b32_e32 v166, 0, v35, vcc
	v_exp_f32_e32 v35, v43
	v_or_b32_e32 v36, 49, v150
	v_cndmask_b32_e64 v59, 0, v34, s[12:13]
	v_exp_f32_e32 v34, v60
	v_cmp_lt_u32_e32 vcc, v36, v137
	s_or_b64 vcc, s[64:65], vcc
	v_or_b32_e32 v36, 50, v150
	v_cndmask_b32_e32 v167, 0, v35, vcc
	v_exp_f32_e32 v35, v44
	v_cndmask_b32_e64 v60, 0, v34, s[16:17]
	v_exp_f32_e32 v34, v61
	v_cmp_lt_u32_e32 vcc, v36, v137
	s_or_b64 vcc, s[64:65], vcc
	v_or_b32_e32 v36, 51, v150
	v_cndmask_b32_e32 v168, 0, v35, vcc
	v_exp_f32_e32 v35, v45
	v_cndmask_b32_e64 v61, 0, v34, s[14:15]
	v_exp_f32_e32 v34, v62
	v_cmp_lt_u32_e32 vcc, v36, v137
	s_or_b64 vcc, s[64:65], vcc
	v_or_b32_e32 v36, 56, v150
	v_cndmask_b32_e32 v172, 0, v35, vcc
	v_exp_f32_e32 v35, v46
	v_cndmask_b32_e64 v46, 0, v34, s[22:23]
	v_exp_f32_e32 v34, v63
	v_cmp_lt_u32_e32 vcc, v36, v137
	s_or_b64 vcc, s[64:65], vcc
	v_or_b32_e32 v36, 57, v150
	v_cndmask_b32_e32 v62, 0, v35, vcc
	v_exp_f32_e32 v35, v47
	v_cndmask_b32_e64 v47, 0, v34, s[20:21]
	v_exp_f32_e32 v34, v64
	v_cmp_lt_u32_e32 vcc, v36, v137
	s_or_b64 vcc, s[64:65], vcc
	v_exp_f32_e32 v38, v48
	v_cndmask_b32_e32 v63, 0, v35, vcc
	v_or_b32_e32 v35, 58, v150
	v_cmp_lt_u32_e32 vcc, v35, v137
	v_cndmask_b32_e64 v48, 0, v34, s[24:25]
	ds_read_b128 v[34:37], v0 offset:18432
	ds_read_b128 v[42:45], v0 offset:18464
	s_or_b64 vcc, s[64:65], vcc
	v_cndmask_b32_e32 v64, 0, v38, vcc
	v_cvt_pk_bf16_f32 v38, v50, v51
	v_cvt_pk_bf16_f32 v39, v52, v53
	v_cvt_pk_bf16_f32 v40, v54, v55
	v_cvt_pk_bf16_f32 v41, v56, v41
	v_exp_f32_e32 v54, v49
	ds_read_b128 v[50:53], v0 offset:18528
	s_waitcnt lgkmcnt(2)
	v_mfma_f32_32x32x16_bf16 v[18:33], v[34:37], v[38:41], v[18:33]
	v_cndmask_b32_e64 v37, 0, v65, s[18:19]
	v_cvt_pk_bf16_f32 v34, v58, v59
	v_cvt_pk_bf16_f32 v35, v60, v61
	v_cvt_pk_bf16_f32 v36, v46, v47
	v_cvt_pk_bf16_f32 v37, v48, v37
	ds_read_b128 v[46:49], v0 offset:18496
	s_waitcnt lgkmcnt(2)
	v_mfma_f32_32x32x16_bf16 v[18:33], v[42:45], v[34:37], v[18:33]
	v_or_b32_e32 v42, 59, v150
	v_cmp_lt_u32_e32 vcc, v42, v137
	v_cvt_pk_bf16_f32 v42, v131, v158
	v_cvt_pk_bf16_f32 v43, v159, v162
	v_cvt_pk_bf16_f32 v44, v163, v164
	v_cvt_pk_bf16_f32 v45, v165, v57
	s_or_b64 vcc, s[64:65], vcc
	s_waitcnt lgkmcnt(0)
	v_mfma_f32_32x32x16_bf16 v[18:33], v[46:49], v[42:45], v[18:33]
	v_cndmask_b32_e32 v49, 0, v54, vcc
	ds_read_b128 v[54:57], v0 offset:23040
	v_cvt_pk_bf16_f32 v46, v166, v167
	v_cvt_pk_bf16_f32 v47, v168, v172
	v_cvt_pk_bf16_f32 v48, v62, v63
	v_cvt_pk_bf16_f32 v49, v64, v49
	s_nop 1
	v_mfma_f32_32x32x16_bf16 v[18:33], v[50:53], v[46:49], v[18:33]
	v_add_f32_e32 v50, v151, v130
	v_add_f32_e32 v50, v153, v50
	v_add_f32_e32 v50, v152, v50
	v_add_f32_e32 v50, v154, v50
	v_add_f32_e32 v50, v157, v50
	v_add_f32_e32 v58, v160, v50
	ds_read_b128 v[50:53], v0 offset:23072
	s_waitcnt lgkmcnt(1)
	v_mfma_f32_32x32x16_bf16 v[2:17], v[54:57], v[38:41], v[2:17]
	v_add_f32_e32 v38, v155, v58
	v_add_f32_e32 v38, v161, v38
	v_add_f32_e32 v38, v169, v38
	v_add_f32_e32 v38, v171, v38
	v_add_f32_e32 v38, v170, v38
	v_add_f32_e32 v54, v188, v38
	ds_read_b128 v[38:41], v0 offset:23104
	s_waitcnt lgkmcnt(1)
	v_mfma_f32_32x32x16_bf16 v[2:17], v[50:53], v[34:37], v[2:17]
	v_add_f32_e32 v34, v189, v54
	v_add_f32_e32 v34, v191, v34
	v_add_f32_e32 v34, v190, v34
	v_add_f32_e32 v34, v192, v34
	v_add_f32_e32 v34, v193, v34
	v_add_f32_e32 v50, v132, v34
	ds_read_b128 v[34:37], v0 offset:23136
	s_waitcnt lgkmcnt(1)
	v_mfma_f32_32x32x16_bf16 v[2:17], v[38:41], v[42:45], v[2:17]
	v_add_f32_e32 v0, v194, v50
	v_add_f32_e32 v0, v133, v0
	v_mov_b32_e32 v38, v0
	s_nop 1
	v_permlane32_swap_b32_e32 v0, v38
	v_add_f32_e32 v0, v0, v38
	v_add_f32_e32 v149, v149, v0
	s_waitcnt lgkmcnt(0)
	v_mfma_f32_32x32x16_bf16 v[2:17], v[34:37], v[46:49], v[2:17]
	v_cmp_gt_f32_e32 vcc, s82, v149
	s_cmp_eq_u64 vcc, exec
	s_cselect_b64 s[6:7], -1, 0

; #define LAS __attribute__((address_space(3)))
; __device__ __forceinline__ int crow(int r, int hi) { return (r & 3) + 8 * (r >> 2) + 4 * hi; }
; #define MFMA32(a, b, c) __builtin_amdgcn_mfma_f32_32x32x16_bf16((a), (b), (c), 0, 0, 0)
; #define ATT_LOAD(set_, kt_) do { kreg[set_] = *(const GAS u32x4*)(ksrc + (size_t)(kt_) * 64 * 2048); \
;         _Pragma("unroll") for (int i_ = 0; i_ < NVC; ++i_) vreg[set_][i_] = *(const GAS u32x4*)(vsrc + (size_t)i_ * 64 * SEQ + (kt_) * 64); } while (0)
; template <int MODE, int DV> ...
;     ...
;         ATT_LOAD(hh, (kt - 2 > 0) ? kt - 2 : 0);
;         const int k0 = kt * 64;
;         const LAS unsigned char* sb = lds + hh * SB2_STAGE;
;         const bool active = ((MODE == 0) ? (k0 <= tw0 + 31) : (k0 < tw0 + 31)) && !wdone;
;         if (active) {
;             f32x16 p0, p1;
;             if (MODE == 0) {
;                 const float bb = slope2 * (float)(k0 + 4 * hi - t) - mrun;
; #pragma unroll
;                 for (int r = 0; r < 16; ++r) { const float c = __builtin_fmaf(slope2, (float)((r & 3) + 8 * (r >> 2)), bb); p0[r] = c; p1[r] = __builtin_fmaf(slope2, 32.0f, c); }
;             } else {
; #pragma unroll
;                 for (int r = 0; r < 16; ++r) { p0[r] = 0.f; p1[r] = 0.f; }
;             }
; #pragma unroll
;             for (int ds = 0; ds < 4; ++ds) {
;                 const bf16x8 k0f = *(const LAS bf16x8*)(sb + koff + ds * 32);
;                 const bf16x8 k1f = *(const LAS bf16x8*)(sb + koff + 32 * KSTR + ds * 32);
;                 p0 = MFMA32(k0f, qf[ds], p0); p1 = MFMA32(k1f, qf[ds], p1);
;     ...
;                 for (int r = 0; r < 16; ++r) {
;                     { const float z = p0[r]; const float e = __builtin_amdgcn_exp2f(-fabsf(z)); const float sp = fmaxf(-z, 0.f) + __builtin_amdgcn_logf(1.0f + e);
;                       const float lb = -sp; float lm = lb - z; if (diag && !(k0 + crow(r, hi) < t)) lm = 0.f; l0[r] = lm; ts += lm; p0[r] = lb + carry; }
;                     { const float z = p1[r]; const float e = __builtin_amdgcn_exp2f(-fabsf(z)); const float sp = fmaxf(-z, 0.f) + __builtin_amdgcn_logf(1.0f + e);
;                       const float lb = -sp; float lm = lb - z; if (diag && !(k0 + 32 + crow(r, hi) < t)) lm = 0.f; l1[r] = lm; ts += lm; p1[r] = lb + carry; }
.LBB0_454:
	v_sub_u32_e64 v0, s88, 2 clamp
	v_lshlrev_b64 v[34:35], 18, v[0:1]
	v_lshl_add_u64 v[34:35], v[126:127], 0, v[34:35]
	v_lshlrev_b32_e32 v0, 7, v0
	v_lshl_add_u64 v[36:37], v[128:129], 0, v[0:1]
	global_load_dwordx4 v[86:89], v[34:35], off offset:3072
	global_load_dwordx4 v[82:85], v[36:37], off
	v_add_co_u32_e32 v34, vcc, 0x20000, v34
	s_lshl_b32 s56, s88, 6
	s_nop 0
	v_addc_co_u32_e32 v35, vcc, 0, v35, vcc
	global_load_dwordx4 v[90:93], v[34:35], off offset:3072
	v_add_co_u32_e32 v34, vcc, 0x80000, v36
	s_cmp_ge_u32 s56, s90
	s_nop 0
	v_addc_co_u32_e32 v35, vcc, 0, v37, vcc
	global_load_dwordx4 v[94:97], v[34:35], off
	s_cselect_b64 s[8:9], -1, 0
	s_or_b64 s[8:9], s[8:9], s[6:7]
	s_and_b64 vcc, exec, s[8:9]
	s_cbranch_vccnz .LBB0_456
	v_add_u32_e32 v0, 0, v146
	ds_read_b128 v[196:199], v0 offset:36864
	ds_read_b128 v[200:203], v0 offset:36896
	ds_read_b128 v[204:207], v0 offset:41472
	ds_read_b128 v[208:211], v0 offset:41504
	ds_read_b128 v[212:215], v0 offset:36928
	ds_read_b128 v[216:219], v0 offset:36960
	ds_read_b128 v[220:223], v0 offset:41536
	ds_read_b128 v[224:227], v0 offset:41568
	s_or_b32 s3, s56, 63
	s_cmp_lt_u32 s3, s87
	s_cselect_b64 s[66:67], -1, 0
	s_waitcnt lgkmcnt(7)
	v_mfma_f32_32x32x16_bf16 v[50:65], v[196:199], v[66:69], 0
	v_or_b32_e32 v166, s56, v148
	v_cmp_lt_u32_e64 s[6:7], v166, v137
	s_or_b64 s[6:7], s[66:67], s[6:7]
	s_mov_b32 s38, s36
	s_mov_b32 s39, s36
	s_mov_b32 s37, s36
	s_waitcnt lgkmcnt(5)
	v_mfma_f32_32x32x16_bf16 v[34:49], v[204:207], v[66:69], 0
	s_waitcnt lgkmcnt(6)
	v_mfma_f32_32x32x16_bf16 v[50:65], v[200:203], v[70:73], v[50:65]
	s_waitcnt lgkmcnt(4)
	v_mfma_f32_32x32x16_bf16 v[34:49], v[208:211], v[70:73], v[34:49]
	s_waitcnt lgkmcnt(3)
	v_mfma_f32_32x32x16_bf16 v[50:65], v[212:215], v[74:77], v[50:65]
	s_waitcnt lgkmcnt(1)
	v_mfma_f32_32x32x16_bf16 v[34:49], v[220:223], v[74:77], v[34:49]
	s_waitcnt lgkmcnt(2)
	v_mfma_f32_32x32x16_bf16 v[50:65], v[216:219], v[78:81], v[50:65]
	v_or_b32_e32 v150, s56, v139
	v_or_b32_e32 v151, 1, v150
	v_cmp_lt_u32_e64 s[8:9], v151, v137
	s_or_b64 s[8:9], s[66:67], s[8:9]
	v_cmp_lt_u32_e32 vcc, v150, v137
	s_or_b64 vcc, s[66:67], vcc
	s_nop 5
	v_exp_f32_e64 v131, -|v50|
	s_waitcnt lgkmcnt(0)
	v_mfma_f32_32x32x16_bf16 v[34:49], v[224:227], v[78:81], v[34:49]
	v_max_f32_e64 v130, -v50, -v50
	v_max_f32_e32 v130, 0, v130
	v_add_f32_e32 v131, 1.0, v131
	v_log_f32_e32 v132, v131
	v_max_f32_e64 v169, -v61, -v61
	s_nop 6
	v_max_f32_e64 v133, -v34, -v34
	v_max_f32_e32 v152, 0, v133
	v_exp_f32_e64 v133, -|v51|
	v_exp_f32_e64 v131, -|v34|
	v_add_f32_e32 v133, 1.0, v133
	v_log_f32_e32 v133, v133
	v_add_f32_e32 v131, 1.0, v131
	v_log_f32_e32 v154, v131
	v_max_f32_e64 v131, -v51, -v51
	v_max_f32_e32 v131, 0, v131
	v_pk_add_f32 v[132:133], v[130:131], v[132:133]
	v_exp_f32_e64 v130, -|v35|
	v_sub_f32_e64 v51, -v133, v51
	v_cndmask_b32_e64 v165, 0, v51, s[8:9]
	v_max_f32_e64 v51, -v35, -v35
	v_add_f32_e32 v130, 1.0, v130
	v_log_f32_e32 v155, v130
	v_max_f32_e32 v153, 0, v51
	v_or_b32_e32 v51, 1, v166
	v_cmp_lt_u32_e64 s[8:9], v51, v137
	v_pk_add_f32 v[130:131], v[152:153], v[154:155]
	v_sub_f32_e64 v50, -v132, v50
	v_sub_f32_e64 v34, -v130, v34
	v_cndmask_b32_e64 v158, 0, v34, s[6:7]
	v_sub_f32_e64 v35, -v131, v35
	s_or_b64 s[6:7], s[66:67], s[8:9]
	v_cndmask_b32_e64 v159, 0, v35, s[6:7]
	v_exp_f32_e64 v35, -|v52|
	v_cndmask_b32_e32 v164, 0, v50, vcc
	v_exp_f32_e64 v51, -|v36|
	v_add_f32_e32 v50, 0, v164
	v_add_f32_e32 v35, 1.0, v35
	v_add_f32_e32 v34, v50, v158
	v_log_f32_e32 v50, v35
	v_or_b32_e32 v35, 2, v150
	v_cmp_lt_u32_e64 s[6:7], v35, v137
	v_max_f32_e64 v35, -v36, -v36
	v_max_f32_e32 v152, 0, v35
	v_add_f32_e32 v35, 1.0, v51
	v_log_f32_e32 v154, v35
	v_exp_f32_e64 v35, -|v53|
	v_or_b32_e32 v51, 2, v166
	v_cmp_lt_u32_e64 s[8:9], v51, v137
	v_add_f32_e32 v34, v165, v34
	v_add_f32_e32 v35, 1.0, v35
	v_log_f32_e32 v51, v35
	v_add_f32_e32 v151, v159, v34
	v_max_f32_e64 v34, -v52, -v52
	v_max_f32_e64 v153, -v53, -v53
	v_max_f32_e32 v34, 0, v34
	v_max_f32_e32 v35, 0, v153
	v_pk_add_f32 v[50:51], v[34:35], v[50:51]
	v_exp_f32_e64 v35, -|v37|
	v_or_b32_e32 v153, 3, v150
	v_cmp_lt_u32_e64 s[10:11], v153, v137
	v_sub_f32_e64 v34, -v50, v52
	v_add_f32_e32 v35, 1.0, v35
	s_or_b64 s[6:7], s[66:67], s[6:7]
	v_log_f32_e32 v155, v35
	v_cndmask_b32_e64 v180, 0, v34, s[6:7]
	v_sub_f32_e64 v34, -v51, v53
	s_or_b64 s[6:7], s[66:67], s[10:11]
	v_cndmask_b32_e64 v163, 0, v34, s[6:7]
	v_max_f32_e64 v34, -v37, -v37
	v_max_f32_e32 v153, 0, v34
	v_or_b32_e32 v34, 3, v166
	v_cmp_lt_u32_e64 s[6:7], v34, v137
	v_pk_add_f32 v[34:35], v[152:153], v[154:155]
	s_or_b64 s[8:9], s[66:67], s[8:9]
	v_sub_f32_e64 v36, -v34, v36
	v_cndmask_b32_e64 v167, 0, v36, s[8:9]
	v_sub_f32_e64 v36, -v35, v37
	v_exp_f32_e64 v37, -|v54|
	v_exp_f32_e64 v53, -|v38|
	s_or_b64 s[6:7], s[66:67], s[6:7]
	v_cndmask_b32_e64 v168, 0, v36, s[6:7]
	v_add_f32_e32 v37, 1.0, v37
	v_log_f32_e32 v52, v37
	v_or_b32_e32 v37, 8, v150
	v_cmp_lt_u32_e64 s[6:7], v37, v137
	v_max_f32_e64 v37, -v38, -v38
	v_max_f32_e32 v152, 0, v37
	v_add_f32_e32 v37, 1.0, v53
	v_log_f32_e32 v154, v37
	v_exp_f32_e64 v37, -|v55|
	v_or_b32_e32 v53, 8, v166
	v_cmp_lt_u32_e64 s[8:9], v53, v137
	v_add_f32_e32 v162, v180, v151
	v_add_f32_e32 v37, 1.0, v37
	v_log_f32_e32 v53, v37
	v_max_f32_e64 v36, -v54, -v54
	v_max_f32_e64 v151, -v55, -v55
	v_max_f32_e32 v36, 0, v36
	v_max_f32_e32 v37, 0, v151
	v_pk_add_f32 v[52:53], v[36:37], v[52:53]
	v_exp_f32_e64 v37, -|v39|
	v_or_b32_e32 v151, 9, v150
	v_cmp_lt_u32_e64 s[10:11], v151, v137
	v_sub_f32_e64 v36, -v52, v54
	v_add_f32_e32 v37, 1.0, v37
	s_or_b64 s[6:7], s[66:67], s[6:7]
	v_log_f32_e32 v155, v37
; __device__ __forceinline__ int crow(int r, int hi) { return (r & 3) + 8 * (r >> 2) + 4 * hi; }
; template <int MODE, int DV> ...
;     ...
;                 for (int r = 0; r < 16; ++r) {
;                     { const float z = p0[r]; const float e = __builtin_amdgcn_exp2f(-fabsf(z)); const float sp = fmaxf(-z, 0.f) + __builtin_amdgcn_logf(1.0f + e);
;                       const float lb = -sp; float lm = lb - z; if (diag && !(k0 + crow(r, hi) < t)) lm = 0.f; l0[r] = lm; ts += lm; p0[r] = lb + carry; }
;                     { const float z = p1[r]; const float e = __builtin_amdgcn_exp2f(-fabsf(z)); const float sp = fmaxf(-z, 0.f) + __builtin_amdgcn_logf(1.0f + e);
;                       const float lb = -sp; float lm = lb - z; if (diag && !(k0 + 32 + crow(r, hi) < t)) lm = 0.f; l1[r] = lm; ts += lm; p1[r] = lb + carry; }
;                 }
	v_cndmask_b32_e64 v184, 0, v36, s[6:7]
	v_sub_f32_e64 v36, -v53, v55
	s_or_b64 s[6:7], s[66:67], s[10:11]
	v_cndmask_b32_e64 v185, 0, v36, s[6:7]
	v_max_f32_e64 v36, -v39, -v39
	v_max_f32_e32 v153, 0, v36
	v_or_b32_e32 v36, 9, v166
	v_cmp_lt_u32_e64 s[10:11], v36, v137
	v_pk_add_f32 v[36:37], v[152:153], v[154:155]
	s_or_b64 s[8:9], s[66:67], s[8:9]
	v_sub_f32_e64 v38, -v36, v38
	v_cndmask_b32_e64 v186, 0, v38, s[8:9]
	v_sub_f32_e64 v38, -v37, v39
	v_exp_f32_e64 v39, -|v56|
	v_exp_f32_e64 v55, -|v40|
	s_or_b64 s[8:9], s[66:67], s[10:11]
	v_cndmask_b32_e64 v187, 0, v38, s[8:9]
	v_add_f32_e32 v39, 1.0, v39
	v_log_f32_e32 v54, v39
	v_or_b32_e32 v39, 10, v150
	v_cmp_lt_u32_e64 s[8:9], v39, v137
	v_max_f32_e64 v39, -v40, -v40
	v_max_f32_e32 v154, 0, v39
	v_add_f32_e32 v39, 1.0, v55
	v_log_f32_e32 v160, v39
	v_exp_f32_e64 v39, -|v57|
	v_or_b32_e32 v55, 10, v166
	v_cmp_lt_u32_e64 s[12:13], v55, v137
	v_max_f32_e64 v38, -v56, -v56
	v_add_f32_e32 v39, 1.0, v39
	v_log_f32_e32 v55, v39
	v_max_f32_e64 v151, -v57, -v57
	v_max_f32_e32 v38, 0, v38
	v_max_f32_e32 v39, 0, v151
	v_pk_add_f32 v[54:55], v[38:39], v[54:55]
	v_exp_f32_e64 v39, -|v41|
	v_or_b32_e32 v151, 11, v150
	v_cmp_lt_u32_e64 s[14:15], v151, v137
	v_sub_f32_e64 v38, -v54, v56
	v_add_f32_e32 v39, 1.0, v39
	s_or_b64 s[10:11], s[66:67], s[8:9]
	v_log_f32_e32 v161, v39
	v_cndmask_b32_e64 v151, 0, v38, s[10:11]
	v_sub_f32_e64 v38, -v55, v57
	s_or_b64 s[8:9], s[66:67], s[14:15]
	v_cndmask_b32_e64 v152, 0, v38, s[8:9]
	v_max_f32_e64 v38, -v41, -v41
	v_max_f32_e32 v155, 0, v38
	v_or_b32_e32 v38, 11, v166
	v_cmp_lt_u32_e64 s[14:15], v38, v137
	v_pk_add_f32 v[38:39], v[154:155], v[160:161]
	s_or_b64 s[12:13], s[66:67], s[12:13]
	v_sub_f32_e64 v40, -v38, v40
	v_cndmask_b32_e64 v153, 0, v40, s[12:13]
	v_sub_f32_e64 v40, -v39, v41
	v_exp_f32_e64 v41, -|v58|
	v_exp_f32_e64 v57, -|v42|
	s_or_b64 s[12:13], s[66:67], s[14:15]
	v_cndmask_b32_e64 v154, 0, v40, s[12:13]
	v_add_f32_e32 v41, 1.0, v41
	v_log_f32_e32 v56, v41
	v_or_b32_e32 v41, 16, v150
	v_cmp_lt_u32_e64 s[12:13], v41, v137
	v_max_f32_e64 v41, -v42, -v42
	v_max_f32_e32 v160, 0, v41
	v_add_f32_e32 v41, 1.0, v57
	v_log_f32_e32 v170, v41
	v_exp_f32_e64 v41, -|v59|
	v_or_b32_e32 v57, 16, v166
	v_cmp_lt_u32_e64 s[14:15], v57, v137
	v_max_f32_e64 v40, -v58, -v58
	v_add_f32_e32 v41, 1.0, v41
	v_log_f32_e32 v57, v41
	v_max_f32_e64 v155, -v59, -v59
	v_max_f32_e32 v40, 0, v40
	v_max_f32_e32 v41, 0, v155
	v_pk_add_f32 v[56:57], v[40:41], v[56:57]
	v_exp_f32_e64 v41, -|v43|
	v_or_b32_e32 v155, 17, v150
	v_cmp_lt_u32_e64 s[16:17], v155, v137
	v_sub_f32_e64 v40, -v56, v58
	v_add_f32_e32 v41, 1.0, v41
	s_or_b64 s[12:13], s[66:67], s[12:13]
	v_log_f32_e32 v171, v41
	v_cndmask_b32_e64 v157, 0, v40, s[12:13]
	v_sub_f32_e64 v40, -v57, v59
	s_or_b64 s[12:13], s[66:67], s[16:17]
	v_cndmask_b32_e64 v155, 0, v40, s[12:13]
	v_max_f32_e64 v40, -v43, -v43
	v_max_f32_e32 v161, 0, v40
	v_or_b32_e32 v40, 17, v166
	v_cmp_lt_u32_e64 s[16:17], v40, v137
	v_pk_add_f32 v[40:41], v[160:161], v[170:171]
	s_or_b64 s[14:15], s[66:67], s[14:15]
	v_sub_f32_e64 v42, -v40, v42
	v_cndmask_b32_e64 v160, 0, v42, s[14:15]
	v_sub_f32_e64 v42, -v41, v43
	v_exp_f32_e64 v43, -|v60|
	v_exp_f32_e64 v59, -|v44|
	s_or_b64 s[14:15], s[66:67], s[16:17]
	v_cndmask_b32_e64 v161, 0, v42, s[14:15]
	v_add_f32_e32 v43, 1.0, v43
	v_log_f32_e32 v58, v43
	v_or_b32_e32 v43, 18, v150
	v_cmp_lt_u32_e64 s[14:15], v43, v137
	v_max_f32_e64 v43, -v44, -v44
	v_max_f32_e32 v172, 0, v43
	v_add_f32_e32 v43, 1.0, v59
	v_log_f32_e32 v174, v43
	v_exp_f32_e64 v43, -|v61|
	v_or_b32_e32 v59, 18, v166
	v_cmp_lt_u32_e64 s[18:19], v59, v137
	v_max_f32_e64 v42, -v60, -v60
	v_add_f32_e32 v43, 1.0, v43
	v_log_f32_e32 v59, v43
	v_max_f32_e32 v42, 0, v42
	v_max_f32_e32 v43, 0, v169
	v_or_b32_e32 v169, 19, v150
	v_pk_add_f32 v[42:43], v[42:43], v[58:59]
	v_exp_f32_e64 v59, -|v45|
	v_cmp_lt_u32_e64 s[20:21], v169, v137
	v_sub_f32_e64 v58, -v42, v60
	s_or_b64 s[16:17], s[66:67], s[14:15]
	v_add_f32_e32 v59, 1.0, v59
	v_log_f32_e32 v175, v59
	v_cndmask_b32_e64 v169, 0, v58, s[16:17]
	v_sub_f32_e64 v58, -v43, v61
	s_or_b64 s[14:15], s[66:67], s[20:21]
	v_cndmask_b32_e64 v170, 0, v58, s[14:15]
	v_max_f32_e64 v58, -v45, -v45
	v_max_f32_e32 v173, 0, v58
	v_pk_add_f32 v[172:173], v[172:173], v[174:175]
	s_or_b64 s[18:19], s[66:67], s[18:19]
	v_sub_f32_e64 v44, -v172, v44
	v_cndmask_b32_e64 v171, 0, v44, s[18:19]
	v_sub_f32_e64 v44, -v173, v45
	v_exp_f32_e64 v45, -|v62|
	v_or_b32_e32 v58, 19, v166
	v_exp_f32_e64 v59, -|v46|
	v_cmp_lt_u32_e64 s[20:21], v58, v137
	v_add_f32_e32 v45, 1.0, v45
	s_or_b64 s[18:19], s[66:67], s[20:21]
	v_log_f32_e32 v58, v45
	v_or_b32_e32 v45, 24, v150
	v_cndmask_b32_e64 v188, 0, v44, s[18:19]
	v_cmp_lt_u32_e64 s[18:19], v45, v137
	v_max_f32_e64 v45, -v46, -v46
	v_max_f32_e32 v60, 0, v45
	v_add_f32_e32 v45, 1.0, v59
	v_log_f32_e32 v174, v45
	v_exp_f32_e64 v45, -|v63|
	v_or_b32_e32 v59, 24, v166
	v_cmp_lt_u32_e64 s[24:25], v59, v137
	v_max_f32_e64 v44, -v62, -v62
	v_add_f32_e32 v45, 1.0, v45
	v_log_f32_e32 v59, v45
	v_max_f32_e64 v61, -v63, -v63
	v_max_f32_e32 v44, 0, v44
	v_max_f32_e32 v45, 0, v61
	v_pk_add_f32 v[44:45], v[44:45], v[58:59]
	v_exp_f32_e64 v59, -|v47|
	v_or_b32_e32 v61, 25, v150
	v_cmp_lt_u32_e64 s[20:21], v61, v137
	v_sub_f32_e64 v58, -v44, v62
	v_add_f32_e32 v59, 1.0, v59
	s_or_b64 s[22:23], s[66:67], s[18:19]
	v_log_f32_e32 v175, v59
	v_cndmask_b32_e64 v189, 0, v58, s[22:23]
	v_sub_f32_e64 v58, -v45, v63
	s_or_b64 s[20:21], s[66:67], s[20:21]
	v_cndmask_b32_e64 v190, 0, v58, s[20:21]
	v_max_f32_e64 v58, -v47, -v47
	v_max_f32_e32 v61, 0, v58
	v_pk_add_f32 v[174:175], v[60:61], v[174:175]
; __device__ __forceinline__ int crow(int r, int hi) { return (r & 3) + 8 * (r >> 2) + 4 * hi; }
; #define MFMA32(a, b, c) __builtin_amdgcn_mfma_f32_32x32x16_bf16((a), (b), (c), 0, 0, 0)
; template <int MODE, int DV> ...
;     ...
;                 for (int r = 0; r < 16; ++r) {
;                     { const float z = p0[r]; const float e = __builtin_amdgcn_exp2f(-fabsf(z)); const float sp = fmaxf(-z, 0.f) + __builtin_amdgcn_logf(1.0f + e);
;                       const float lb = -sp; float lm = lb - z; if (diag && !(k0 + crow(r, hi) < t)) lm = 0.f; l0[r] = lm; ts += lm; p0[r] = lb + carry; }
;                     { const float z = p1[r]; const float e = __builtin_amdgcn_exp2f(-fabsf(z)); const float sp = fmaxf(-z, 0.f) + __builtin_amdgcn_logf(1.0f + e);
;                       const float lb = -sp; float lm = lb - z; if (diag && !(k0 + 32 + crow(r, hi) < t)) lm = 0.f; l1[r] = lm; ts += lm; p1[r] = lb + carry; }
;                 }
;                 const bf16x8 L0a = pack8(l0, 0), L0b = pack8(l0, 8), L1a = pack8(l1, 0), L1b = pack8(l1, 8);
;                 p0 = MFMA32(ut0, L0a, p0); p0 = MFMA32(ut1, L0b, p0); p0 = MFMA32(uone, L1a, p0); p0 = MFMA32(uone, L1b, p0);
;                 p1 = MFMA32(ut0, L1a, p1); p1 = MFMA32(ut1, L1b, p1);
; #pragma unroll
;                 for (int r = 0; r < 16; ++r) {
;                     float a0 = __builtin_amdgcn_exp2f(p0[r]), a1 = __builtin_amdgcn_exp2f(p1[r]);
;                     if (diag) { if (!(k0 + crow(r, hi) < t)) a0 = 0.f; if (!(k0 + 32 + crow(r, hi) < t)) a1 = 0.f; }
;                     p0[r] = a0; p1[r] = a1;
;                 }
	s_or_b64 s[24:25], s[66:67], s[24:25]
	v_sub_f32_e64 v46, -v174, v46
	v_cndmask_b32_e64 v191, 0, v46, s[24:25]
	v_sub_f32_e64 v46, -v175, v47
	v_exp_f32_e64 v47, -|v64|
	v_or_b32_e32 v58, 25, v166
	v_exp_f32_e64 v59, -|v48|
	v_cmp_lt_u32_e64 s[18:19], v58, v137
	v_add_f32_e32 v47, 1.0, v47
	s_or_b64 s[18:19], s[66:67], s[18:19]
	v_log_f32_e32 v58, v47
	v_or_b32_e32 v47, 26, v150
	v_cndmask_b32_e64 v192, 0, v46, s[18:19]
	v_cmp_lt_u32_e64 s[18:19], v47, v137
	v_max_f32_e64 v47, -v48, -v48
	v_max_f32_e32 v176, 0, v47
	v_add_f32_e32 v47, 1.0, v59
	v_log_f32_e32 v178, v47
	v_exp_f32_e64 v47, -|v65|
	v_or_b32_e32 v59, 26, v166
	v_max_f32_e64 v60, -v65, -v65
	v_cmp_lt_u32_e64 s[28:29], v59, v137
	v_add_f32_e32 v47, 1.0, v47
	v_log_f32_e32 v59, v47
	v_max_f32_e32 v47, 0, v60
	v_or_b32_e32 v60, 27, v150
	v_cmp_lt_u32_e64 s[30:31], v60, v137
	v_sub_f32_e32 v60, v149, v42
	v_exp_f32_e64 v42, -|v49|
	v_max_f32_e64 v46, -v64, -v64
	v_max_f32_e32 v46, 0, v46
	v_sub_f32_e32 v61, v149, v43
	v_add_f32_e32 v42, 1.0, v42
	v_log_f32_e32 v179, v42
	v_max_f32_e64 v43, -v49, -v49
	v_pk_add_f32 v[46:47], v[46:47], v[58:59]
	v_max_f32_e32 v177, 0, v43
	v_or_b32_e32 v42, 27, v166
	v_sub_f32_e64 v58, -v46, v64
	s_or_b64 s[24:25], s[66:67], s[18:19]
	s_or_b64 s[18:19], s[66:67], s[30:31]
	v_cmp_lt_u32_e64 s[30:31], v42, v137
	v_pk_add_f32 v[42:43], v[176:177], v[178:179]
	v_cndmask_b32_e64 v193, 0, v58, s[24:25]
	v_sub_f32_e64 v58, -v47, v65
	v_sub_f32_e32 v62, v149, v44
	v_sub_f32_e64 v44, -v42, v48
	s_or_b64 s[28:29], s[66:67], s[28:29]
	v_cndmask_b32_e64 v194, 0, v58, s[18:19]
	v_sub_f32_e32 v58, v149, v56
	v_sub_f32_e32 v56, v149, v54
	v_sub_f32_e32 v54, v149, v52
	v_sub_f32_e32 v52, v149, v50
	v_sub_f32_e32 v50, v149, v132
	v_cndmask_b32_e64 v132, 0, v44, s[28:29]
	v_sub_f32_e64 v44, -v43, v49
	s_or_b64 s[28:29], s[66:67], s[30:31]
	v_sub_f32_e32 v65, v149, v47
	v_sub_f32_e32 v64, v149, v46
	v_sub_f32_e32 v63, v149, v45
	v_sub_f32_e32 v59, v149, v57
	v_sub_f32_e32 v57, v149, v55
	v_sub_f32_e32 v55, v149, v53
	v_sub_f32_e32 v53, v149, v51
	v_sub_f32_e32 v51, v149, v133
	v_cndmask_b32_e64 v133, 0, v44, s[28:29]
	v_sub_f32_e32 v49, v149, v43
	v_sub_f32_e32 v48, v149, v42
	v_cvt_pk_bf16_f32 v42, v164, v165
	v_cvt_pk_bf16_f32 v43, v180, v163
	v_cvt_pk_bf16_f32 v44, v184, v185
	v_cvt_pk_bf16_f32 v45, v151, v152
	v_sub_f32_e32 v47, v149, v175
	v_sub_f32_e32 v46, v149, v174
	v_mfma_f32_32x32x16_bf16 v[50:65], v[98:101], v[42:45], v[50:65]
	v_sub_f32_e32 v45, v149, v173
	v_sub_f32_e32 v44, v149, v172
	v_cvt_pk_bf16_f32 v172, v157, v155
	v_cvt_pk_bf16_f32 v173, v169, v170
	v_cvt_pk_bf16_f32 v174, v189, v190
	v_cvt_pk_bf16_f32 v175, v193, v194
	v_cvt_pk_bf16_f32 v176, v158, v159
	v_cvt_pk_bf16_f32 v177, v167, v168
	v_mfma_f32_32x32x16_bf16 v[50:65], v[102:105], v[172:175], v[50:65]
	v_mov_b64_e32 v[174:175], s[38:39]
	v_mov_b64_e32 v[172:173], s[36:37]
	v_cvt_pk_bf16_f32 v178, v186, v187
	v_cvt_pk_bf16_f32 v179, v153, v154
	v_sub_f32_e32 v43, v149, v41
	v_sub_f32_e32 v42, v149, v40
	v_sub_f32_e32 v41, v149, v39
	v_mfma_f32_32x32x16_bf16 v[50:65], v[172:175], v[176:179], v[50:65]
	v_sub_f32_e32 v40, v149, v38
	v_sub_f32_e32 v39, v149, v37
	v_sub_f32_e32 v38, v149, v36
	v_sub_f32_e32 v37, v149, v35
	v_sub_f32_e32 v36, v149, v34
	v_sub_f32_e32 v35, v149, v131
	v_sub_f32_e32 v34, v149, v130
	v_cvt_pk_bf16_f32 v180, v160, v161
	v_cvt_pk_bf16_f32 v181, v171, v188
	v_mfma_f32_32x32x16_bf16 v[34:49], v[98:101], v[176:179], v[34:49]
	v_cvt_pk_bf16_f32 v182, v191, v192
	v_cvt_pk_bf16_f32 v183, v132, v133
	v_or_b32_e32 v131, 32, v150
	v_cmp_lt_u32_e64 s[28:29], v131, v137
	v_add_f32_e32 v130, v167, v162
	v_add_f32_e32 v130, v163, v130
	v_add_f32_e32 v130, v168, v130
	v_mfma_f32_32x32x16_bf16 v[50:65], v[172:175], v[180:183], v[50:65]
	v_add_f32_e32 v130, v184, v130
	v_add_f32_e32 v130, v186, v130
	v_add_f32_e32 v130, v185, v130
	v_add_f32_e32 v130, v187, v130
	v_mfma_f32_32x32x16_bf16 v[34:49], v[102:105], v[180:183], v[34:49]
	s_nop 6
	v_exp_f32_e32 v50, v50
	v_exp_f32_e32 v65, v65
	v_cndmask_b32_e32 v50, 0, v50, vcc
	s_or_b64 vcc, s[66:67], s[28:29]
	s_nop 0
	v_exp_f32_e32 v34, v34
	v_exp_f32_e32 v35, v35
	v_cndmask_b32_e32 v131, 0, v34, vcc
	v_exp_f32_e32 v34, v51
	v_or_b32_e32 v51, s56, v141
	v_cmp_lt_u32_e32 vcc, v51, v137
	v_or_b32_e32 v51, 32, v51
	v_cmp_lt_u32_e64 s[28:29], v51, v137
	s_or_b64 vcc, s[66:67], vcc
	v_cndmask_b32_e32 v51, 0, v34, vcc
	s_or_b64 vcc, s[66:67], s[28:29]
	v_exp_f32_e32 v34, v52
	v_cndmask_b32_e32 v158, 0, v35, vcc
	v_exp_f32_e32 v35, v36
	v_or_b32_e32 v36, s56, v142
	v_cmp_lt_u32_e32 vcc, v36, v137
	v_or_b32_e32 v36, 32, v36
	s_or_b64 vcc, s[66:67], vcc
	v_cmp_lt_u32_e64 s[28:29], v36, v137
	v_cndmask_b32_e32 v52, 0, v34, vcc
	v_exp_f32_e32 v34, v53
	s_or_b64 vcc, s[66:67], s[28:29]
	v_or_b32_e32 v36, s56, v143
	v_cndmask_b32_e32 v159, 0, v35, vcc
	v_exp_f32_e32 v35, v37
	v_cmp_lt_u32_e32 vcc, v36, v137
	v_or_b32_e32 v36, 32, v36
	s_or_b64 vcc, s[66:67], vcc
	v_cmp_lt_u32_e64 s[28:29], v36, v137
	v_cndmask_b32_e32 v53, 0, v34, vcc
	v_exp_f32_e32 v34, v54
	s_or_b64 vcc, s[66:67], s[28:29]
; #define LAS __attribute__((address_space(3)))
; __device__ __forceinline__ int crow(int r, int hi) { return (r & 3) + 8 * (r >> 2) + 4 * hi; }
; #define MFMA32(a, b, c) __builtin_amdgcn_mfma_f32_32x32x16_bf16((a), (b), (c), 0, 0, 0)
; __device__ __forceinline__ float xhalf_sum(float m) { auto rr = __builtin_amdgcn_permlane32_swap(__float_as_uint(m), __float_as_uint(m), false, false); return __uint_as_float(rr[0]) + __uint_as_float(rr[1]); }
; template <int MODE, int DV> ...
;     ...
;                 for (int r = 0; r < 16; ++r) {
;                     float a0 = __builtin_amdgcn_exp2f(p0[r]), a1 = __builtin_amdgcn_exp2f(p1[r]);
;                     if (diag) { if (!(k0 + crow(r, hi) < t)) a0 = 0.f; if (!(k0 + 32 + crow(r, hi) < t)) a1 = 0.f; }
;                     p0[r] = a0; p1[r] = a1;
;                 }
;                 ts = xhalf_sum(ts);
;                 carry += ts;
;                 pf0 = pack8(p0, 0); pf1 = pack8(p0, 8); pf2 = pack8(p1, 0); pf3 = pack8(p1, 8);
;                 wdone = __all(carry < THR) != 0;
;             }
; #pragma unroll
;             for (int d = 0; d < NDB; ++d) {
;                 const LAS unsigned char* vb = sb + 2 * SB2_KB + d * 32 * KSTR + koff;
;                 const bf16x8 v0 = *(const LAS bf16x8*)(vb), v1 = *(const LAS bf16x8*)(vb + 32), v2 = *(const LAS bf16x8*)(vb + 64), v3 = *(const LAS bf16x8*)(vb + 96);
;                 o[d] = MFMA32(v0, pf0, o[d]); o[d] = MFMA32(v1, pf1, o[d]); o[d] = MFMA32(v2, pf2, o[d]); o[d] = MFMA32(v3, pf3, o[d]);
;             }
	v_or_b32_e32 v36, s56, v144
	v_cndmask_b32_e32 v162, 0, v35, vcc
	v_exp_f32_e32 v35, v38
	v_cmp_lt_u32_e32 vcc, v36, v137
	v_or_b32_e32 v36, 32, v36
	s_or_b64 vcc, s[66:67], vcc
	v_cmp_lt_u32_e64 s[28:29], v36, v137
	v_cndmask_b32_e32 v54, 0, v34, vcc
	v_exp_f32_e32 v34, v55
	s_or_b64 vcc, s[66:67], s[28:29]
	v_cndmask_b32_e32 v163, 0, v35, vcc
	v_exp_f32_e32 v35, v39
	v_or_b32_e32 v36, 41, v150
	v_cmp_lt_u32_e32 vcc, v36, v137
	v_cndmask_b32_e64 v55, 0, v34, s[6:7]
	v_exp_f32_e32 v34, v56
	s_or_b64 vcc, s[66:67], vcc
	v_cndmask_b32_e32 v164, 0, v35, vcc
	v_exp_f32_e32 v35, v40
	v_or_b32_e32 v36, 42, v150
	v_cmp_lt_u32_e32 vcc, v36, v137
	v_cndmask_b32_e64 v56, 0, v34, s[10:11]
	v_exp_f32_e32 v34, v57
	s_or_b64 vcc, s[66:67], vcc
	v_cndmask_b32_e32 v165, 0, v35, vcc
	v_exp_f32_e32 v35, v41
	v_or_b32_e32 v36, 43, v150
	v_cmp_lt_u32_e32 vcc, v36, v137
	v_cndmask_b32_e64 v41, 0, v34, s[8:9]
	v_exp_f32_e32 v34, v58
	s_or_b64 vcc, s[66:67], vcc
	v_or_b32_e32 v36, s56, v140
	v_cndmask_b32_e32 v57, 0, v35, vcc
	v_cmp_lt_u32_e32 vcc, v36, v137
	v_exp_f32_e32 v35, v42
	s_or_b64 vcc, s[66:67], vcc
	v_or_b32_e32 v36, 32, v36
	v_cndmask_b32_e32 v58, 0, v34, vcc
	v_exp_f32_e32 v34, v59
	v_cmp_lt_u32_e64 s[6:7], v36, v137
	s_or_b64 vcc, s[66:67], s[6:7]
	v_cndmask_b32_e32 v166, 0, v35, vcc
	v_exp_f32_e32 v35, v43
	v_or_b32_e32 v36, 49, v150
	v_cndmask_b32_e64 v59, 0, v34, s[12:13]
	v_exp_f32_e32 v34, v60
	v_cmp_lt_u32_e32 vcc, v36, v137
	s_or_b64 vcc, s[66:67], vcc
	v_or_b32_e32 v36, 50, v150
	v_cndmask_b32_e32 v167, 0, v35, vcc
	v_exp_f32_e32 v35, v44
	v_cndmask_b32_e64 v60, 0, v34, s[16:17]
	v_exp_f32_e32 v34, v61
	v_cmp_lt_u32_e32 vcc, v36, v137
	s_or_b64 vcc, s[66:67], vcc
	v_or_b32_e32 v36, 51, v150
	v_cndmask_b32_e32 v168, 0, v35, vcc
	v_exp_f32_e32 v35, v45
	v_cndmask_b32_e64 v61, 0, v34, s[14:15]
	v_exp_f32_e32 v34, v62
	v_cmp_lt_u32_e32 vcc, v36, v137
	s_or_b64 vcc, s[66:67], vcc
	v_or_b32_e32 v36, 56, v150
	v_cndmask_b32_e32 v172, 0, v35, vcc
	v_exp_f32_e32 v35, v46
	v_cndmask_b32_e64 v46, 0, v34, s[22:23]
	v_exp_f32_e32 v34, v63
	v_cmp_lt_u32_e32 vcc, v36, v137
	s_or_b64 vcc, s[66:67], vcc
	v_or_b32_e32 v36, 57, v150
	v_cndmask_b32_e32 v62, 0, v35, vcc
	v_exp_f32_e32 v35, v47
	v_cndmask_b32_e64 v47, 0, v34, s[20:21]
	v_exp_f32_e32 v34, v64
	v_cmp_lt_u32_e32 vcc, v36, v137
	s_or_b64 vcc, s[66:67], vcc
	v_exp_f32_e32 v38, v48
	v_cndmask_b32_e32 v63, 0, v35, vcc
	v_or_b32_e32 v35, 58, v150
	v_cmp_lt_u32_e32 vcc, v35, v137
	v_cndmask_b32_e64 v48, 0, v34, s[24:25]
	ds_read_b128 v[34:37], v0 offset:55296
	ds_read_b128 v[42:45], v0 offset:55328
	s_or_b64 vcc, s[66:67], vcc
	v_cndmask_b32_e32 v64, 0, v38, vcc
	v_cvt_pk_bf16_f32 v38, v50, v51
	v_cvt_pk_bf16_f32 v39, v52, v53
	v_cvt_pk_bf16_f32 v40, v54, v55
	v_cvt_pk_bf16_f32 v41, v56, v41
	v_exp_f32_e32 v54, v49
	ds_read_b128 v[50:53], v0 offset:55392
	s_waitcnt lgkmcnt(2)
	v_mfma_f32_32x32x16_bf16 v[18:33], v[34:37], v[38:41], v[18:33]
	v_cndmask_b32_e64 v37, 0, v65, s[18:19]
	v_cvt_pk_bf16_f32 v34, v58, v59
	v_cvt_pk_bf16_f32 v35, v60, v61
	v_cvt_pk_bf16_f32 v36, v46, v47
	v_cvt_pk_bf16_f32 v37, v48, v37
	ds_read_b128 v[46:49], v0 offset:55360
	s_waitcnt lgkmcnt(2)
	v_mfma_f32_32x32x16_bf16 v[18:33], v[42:45], v[34:37], v[18:33]
	v_or_b32_e32 v42, 59, v150
	v_cmp_lt_u32_e32 vcc, v42, v137
	v_cvt_pk_bf16_f32 v42, v131, v158
	v_cvt_pk_bf16_f32 v43, v159, v162
	v_cvt_pk_bf16_f32 v44, v163, v164
	v_cvt_pk_bf16_f32 v45, v165, v57
	s_or_b64 vcc, s[66:67], vcc
	s_waitcnt lgkmcnt(0)
	v_mfma_f32_32x32x16_bf16 v[18:33], v[46:49], v[42:45], v[18:33]
	v_cndmask_b32_e32 v49, 0, v54, vcc
	ds_read_b128 v[54:57], v0 offset:59904
	v_cvt_pk_bf16_f32 v46, v166, v167
	v_cvt_pk_bf16_f32 v47, v168, v172
	v_cvt_pk_bf16_f32 v48, v62, v63
	v_cvt_pk_bf16_f32 v49, v64, v49
	s_nop 1
	v_mfma_f32_32x32x16_bf16 v[18:33], v[50:53], v[46:49], v[18:33]
	v_add_f32_e32 v50, v151, v130
	v_add_f32_e32 v50, v153, v50
	v_add_f32_e32 v50, v152, v50
	v_add_f32_e32 v50, v154, v50
	v_add_f32_e32 v50, v157, v50
	v_add_f32_e32 v58, v160, v50
	ds_read_b128 v[50:53], v0 offset:59936
	s_waitcnt lgkmcnt(1)
	v_mfma_f32_32x32x16_bf16 v[2:17], v[54:57], v[38:41], v[2:17]
	v_add_f32_e32 v38, v155, v58
	v_add_f32_e32 v38, v161, v38
	v_add_f32_e32 v38, v169, v38
	v_add_f32_e32 v38, v171, v38
	v_add_f32_e32 v38, v170, v38
	v_add_f32_e32 v54, v188, v38
	ds_read_b128 v[38:41], v0 offset:59968
	s_waitcnt lgkmcnt(1)
	v_mfma_f32_32x32x16_bf16 v[2:17], v[50:53], v[34:37], v[2:17]
	v_add_f32_e32 v34, v189, v54
	v_add_f32_e32 v34, v191, v34
	v_add_f32_e32 v34, v190, v34
	v_add_f32_e32 v34, v192, v34
	v_add_f32_e32 v34, v193, v34
	v_add_f32_e32 v50, v132, v34
	ds_read_b128 v[34:37], v0 offset:60000
	s_waitcnt lgkmcnt(1)
	v_mfma_f32_32x32x16_bf16 v[2:17], v[38:41], v[42:45], v[2:17]
	v_add_f32_e32 v0, v194, v50
	v_add_f32_e32 v0, v133, v0
	v_mov_b32_e32 v38, v0
	s_nop 1
	v_permlane32_swap_b32_e32 v0, v38
	v_add_f32_e32 v0, v0, v38
	v_add_f32_e32 v149, v149, v0
	s_waitcnt lgkmcnt(0)
	v_mfma_f32_32x32x16_bf16 v[2:17], v[34:37], v[46:49], v[2:17]
	v_cmp_gt_f32_e32 vcc, s82, v149
	s_cmp_eq_u64 vcc, exec
	s_cselect_b64 s[6:7], -1, 0
